# v12 + LN2 row loops (dense and MoE) prefetch two rows ahead: third register set alternating with the row parity
# speedup vs baseline: 1.0042x; 1.0025x over previous
; template <int MODE, bool ROUTE, int H8> ...
;     ...
;         unsigned wq0 = 0u, wq1 = 0u;
;         LN_LOAD(0);
;         for (int r = 0; r < 32; ++r) {
;     ...
;             if (r + 1 < 32) LN_LOAD(r + 1);
.LBB0_1237:
	s_lshl_b32 s24, s2, 5
	s_ashr_i32 s25, s24, 31
	s_lshl_b64 s[42:43], s[24:25], 11
	v_lshl_add_u64 v[84:85], v[102:103], 0, s[42:43]
	s_lshl_b64 s[42:43], s[24:25], 12
	s_lshl_b64 s[24:25], s[24:25], 4
	s_add_u32 s24, s16, s24
	s_addc_u32 s25, s45, s25
	v_lshl_add_u64 v[126:127], v[108:109], 0, s[42:43]
	global_load_dwordx2 v[152:153], v[84:85], off nt
	global_load_dwordx2 v[88:89], v[84:85], off offset:512 nt
	global_load_dwordx2 v[92:93], v[84:85], off offset:1024 nt
	s_nop 0
	global_load_dwordx2 v[84:85], v[84:85], off offset:1536 nt
	s_nop 0
	global_load_dwordx2 v[154:155], v[126:127], off
	global_load_dwordx2 v[90:91], v[126:127], off offset:512
	global_load_dwordx2 v[94:95], v[126:127], off offset:1024
	global_load_dwordx2 v[86:87], v[126:127], off offset:1536
	global_load_dwordx2 v[158:159], v[126:127], off offset:2560
	global_load_dwordx2 v[156:157], v[126:127], off offset:3072
	global_load_dwordx2 v[96:97], v[126:127], off offset:3584
	global_load_dwordx2 v[98:99], v67, s[24:25] offset:4
	global_load_dwordx2 v[160:161], v[126:127], off offset:2048
	s_add_i32 s24, s54, 1
	s_ashr_i32 s25, s24, 31
	s_lshl_b64 s[42:43], s[24:25], 11
	v_lshl_add_u64 v[132:133], v[102:103], 0, s[42:43]
	s_lshl_b64 s[42:43], s[24:25], 12
	v_lshl_add_u64 v[142:143], v[108:109], 0, s[42:43]
	global_load_dwordx2 v[126:127], v[132:133], off nt
	global_load_dwordx2 v[128:129], v[132:133], off offset:512 nt
	global_load_dwordx2 v[130:131], v[132:133], off offset:1024 nt
	s_nop 0
	global_load_dwordx2 v[132:133], v[132:133], off offset:1536 nt
	s_nop 0
	global_load_dwordx2 v[140:141], v[142:143], off
	global_load_dwordx2 v[138:139], v[142:143], off offset:512
	global_load_dwordx2 v[136:137], v[142:143], off offset:1024
	global_load_dwordx2 v[134:135], v[142:143], off offset:1536
	global_load_dwordx2 v[148:149], v[142:143], off offset:2048
	global_load_dwordx2 v[146:147], v[142:143], off offset:2560
	global_load_dwordx2 v[144:145], v[142:143], off offset:3072
	s_nop 0
	global_load_dwordx2 v[142:143], v[142:143], off offset:3584
	s_lshl_b64 s[24:25], s[24:25], 4
	s_add_u32 s24, s16, s24
	s_addc_u32 s25, s45, s25
	global_load_dwordx2 v[150:151], v67, s[24:25] offset:4
	s_mov_b32 s56, 0
	s_waitcnt vmcnt(13)
	s_branch .LBB0_1240
.Lmy_ln2m_tail9:
	s_or_b64 exec, exec, s[24:25]
	s_cmp_eq_u32 s56, 0
	s_cbranch_scc1 .Lmy_ln2m_Lmy_ln2m_tail9_first
	s_cmp_gt_u32 s56, 29
	s_cbranch_scc1 .Lmy_ln2m_Lmy_ln2m_tail9_last
	s_waitcnt vmcnt(31)
	s_branch .Lmy_ln2m_copy
.Lmy_ln2m_Lmy_ln2m_tail9_first:
	s_waitcnt vmcnt(22)
	s_branch .Lmy_ln2m_copy
.Lmy_ln2m_Lmy_ln2m_tail9_last:
	s_waitcnt vmcnt(18)
	s_branch .Lmy_ln2m_copy
.Lmy_ln2m_tail4:
	s_cmp_eq_u32 s56, 0
	s_cbranch_scc1 .Lmy_ln2m_Lmy_ln2m_tail4_first
	s_cmp_gt_u32 s56, 29
	s_cbranch_scc1 .Lmy_ln2m_Lmy_ln2m_tail4_last
	s_waitcnt vmcnt(21)
	s_branch .Lmy_ln2m_copy
.Lmy_ln2m_Lmy_ln2m_tail4_first:
	s_waitcnt vmcnt(17)
	s_branch .Lmy_ln2m_copy
.Lmy_ln2m_Lmy_ln2m_tail4_last:
	s_waitcnt vmcnt(8)
	s_branch .Lmy_ln2m_copy
.LBB0_1238:
	s_or_b64 exec, exec, s[24:25]
.LBB0_1239:
	s_waitcnt vmcnt(0)
.Lmy_ln2m_copy:
	s_bitcmp1_b32 s56, 0
	s_cbranch_scc1 .Lmy_ln2m_copyB
	v_mov_b64_e32 v[84:85], v[132:133]
	v_mov_b64_e32 v[92:93], v[130:131]
	v_mov_b64_e32 v[88:89], v[128:129]
	v_mov_b64_e32 v[152:153], v[126:127]
	v_mov_b64_e32 v[86:87], v[134:135]
	v_mov_b64_e32 v[94:95], v[136:137]
	v_mov_b64_e32 v[90:91], v[138:139]
	v_mov_b64_e32 v[154:155], v[140:141]
	v_mov_b64_e32 v[96:97], v[142:143]
	v_mov_b64_e32 v[156:157], v[144:145]
	v_mov_b64_e32 v[158:159], v[146:147]
	v_mov_b64_e32 v[160:161], v[148:149]
	v_mov_b64_e32 v[98:99], v[150:151]
	s_branch .Lmy_ln2m_next
.Lmy_ln2m_copyB:
	v_mov_b64_e32 v[84:85], v[182:183]
	v_mov_b64_e32 v[92:93], v[180:181]
	v_mov_b64_e32 v[88:89], v[178:179]
	v_mov_b64_e32 v[152:153], v[176:177]
	v_mov_b64_e32 v[86:87], v[184:185]
	v_mov_b64_e32 v[94:95], v[186:187]
	v_mov_b64_e32 v[90:91], v[188:189]
	v_mov_b64_e32 v[154:155], v[190:191]
	v_mov_b64_e32 v[96:97], v[192:193]
	v_mov_b64_e32 v[156:157], v[194:195]
	v_mov_b64_e32 v[158:159], v[196:197]
	v_mov_b64_e32 v[160:161], v[198:199]
	v_mov_b64_e32 v[98:99], v[200:201]
.Lmy_ln2m_next:
	s_add_i32 s56, s56, 1
	s_cmp_eq_u32 s56, 32
	s_cbranch_scc1 .LBB0_1228
.LBB0_1240:
	s_add_i32 s46, s54, s56
	s_cmp_gt_u32 s56, 29
	s_cbranch_scc1 .LBB0_1242
	s_add_i32 s24, s46, 2
	s_bitcmp1_b32 s56, 0
	s_cbranch_scc1 .Lmy_ln2m_ldA
	s_ashr_i32 s25, s24, 31
	s_lshl_b64 s[42:43], s[24:25], 11
	v_lshl_add_u64 v[182:183], v[102:103], 0, s[42:43]
	s_lshl_b64 s[42:43], s[24:25], 12
	v_lshl_add_u64 v[192:193], v[108:109], 0, s[42:43]
	global_load_dwordx2 v[176:177], v[182:183], off nt
	global_load_dwordx2 v[178:179], v[182:183], off offset:512 nt
	global_load_dwordx2 v[180:181], v[182:183], off offset:1024 nt
	s_nop 0
	global_load_dwordx2 v[182:183], v[182:183], off offset:1536 nt
	s_nop 0
	global_load_dwordx2 v[190:191], v[192:193], off
	global_load_dwordx2 v[188:189], v[192:193], off offset:512
	global_load_dwordx2 v[186:187], v[192:193], off offset:1024
	global_load_dwordx2 v[184:185], v[192:193], off offset:1536
	global_load_dwordx2 v[198:199], v[192:193], off offset:2048
	global_load_dwordx2 v[196:197], v[192:193], off offset:2560
	global_load_dwordx2 v[194:195], v[192:193], off offset:3072
	s_nop 0
	global_load_dwordx2 v[192:193], v[192:193], off offset:3584
	s_lshl_b64 s[24:25], s[24:25], 4
	s_add_u32 s24, s16, s24
	s_addc_u32 s25, s45, s25
	global_load_dwordx2 v[200:201], v67, s[24:25] offset:4
	s_branch .LBB0_1242
.Lmy_ln2m_ldA:
	s_ashr_i32 s25, s24, 31
	s_lshl_b64 s[42:43], s[24:25], 11
	v_lshl_add_u64 v[132:133], v[102:103], 0, s[42:43]
	s_lshl_b64 s[42:43], s[24:25], 12
	v_lshl_add_u64 v[142:143], v[108:109], 0, s[42:43]
	global_load_dwordx2 v[126:127], v[132:133], off nt
	global_load_dwordx2 v[128:129], v[132:133], off offset:512 nt
	global_load_dwordx2 v[130:131], v[132:133], off offset:1024 nt
	s_nop 0
	global_load_dwordx2 v[132:133], v[132:133], off offset:1536 nt
	s_nop 0
	global_load_dwordx2 v[140:141], v[142:143], off
	global_load_dwordx2 v[138:139], v[142:143], off offset:512
	global_load_dwordx2 v[136:137], v[142:143], off offset:1024
	global_load_dwordx2 v[134:135], v[142:143], off offset:1536
	global_load_dwordx2 v[148:149], v[142:143], off offset:2048
	global_load_dwordx2 v[146:147], v[142:143], off offset:2560
	global_load_dwordx2 v[144:145], v[142:143], off offset:3072
	s_nop 0
	global_load_dwordx2 v[142:143], v[142:143], off offset:3584
	s_lshl_b64 s[24:25], s[24:25], 4
	s_add_u32 s24, s16, s24
	s_addc_u32 s25, s45, s25
	global_load_dwordx2 v[150:151], v67, s[24:25] offset:4

; template <int MODE, bool ROUTE, int H8> ...
;     ...
;         unsigned wq0 = 0u, wq1 = 0u;
;         LN_LOAD(0);
;         for (int r = 0; r < 32; ++r) {
.LBB0_1275:
	s_lshl_b32 s2, s16, 5
	s_ashr_i32 s3, s2, 31
	s_lshl_b64 s[2:3], s[2:3], 11
	v_lshl_add_u64 v[86:87], v[102:103], 0, s[2:3]
	v_lshl_add_u64 v[98:99], v[104:105], 0, s[2:3]
	global_load_dwordx2 v[92:93], v[86:87], off offset:1024 nt
	global_load_dwordx2 v[84:85], v[86:87], off offset:1536 nt
	global_load_dwordx2 v[96:97], v[86:87], off nt
	global_load_dwordx2 v[88:89], v[86:87], off offset:512 nt
	s_nop 0
	global_load_dwordx2 v[86:87], v[98:99], off offset:1536
	global_load_dwordx2 v[94:95], v[98:99], off offset:1024
	global_load_dwordx2 v[90:91], v[98:99], off offset:512
	s_nop 0
	global_load_dwordx2 v[98:99], v[98:99], off
	s_add_i32 s2, s46, 1
	s_ashr_i32 s3, s2, 31
	s_lshl_b64 s[2:3], s[2:3], 11
	v_lshl_add_u64 v[132:133], v[102:103], 0, s[2:3]
	v_lshl_add_u64 v[134:135], v[104:105], 0, s[2:3]
	global_load_dwordx2 v[126:127], v[132:133], off nt
	global_load_dwordx2 v[128:129], v[132:133], off offset:512 nt
	global_load_dwordx2 v[130:131], v[132:133], off offset:1024 nt
	s_nop 0
	global_load_dwordx2 v[132:133], v[132:133], off offset:1536 nt
	s_nop 0
	global_load_dwordx2 v[140:141], v[134:135], off
	global_load_dwordx2 v[138:139], v[134:135], off offset:512
	global_load_dwordx2 v[136:137], v[134:135], off offset:1024
	s_nop 0
	global_load_dwordx2 v[134:135], v[134:135], off offset:1536
	s_mov_b32 s42, 0
	s_waitcnt vmcnt(8)
	s_branch .LBB0_1278
.Lmy_ln2d_tail9:
	s_or_b64 exec, exec, s[2:3]
	s_cmp_eq_u32 s42, 0
	s_cbranch_scc1 .Lmy_ln2d_Lmy_ln2d_tail9_first
	s_cmp_gt_u32 s42, 29
	s_cbranch_scc1 .Lmy_ln2d_Lmy_ln2d_tail9_last
	s_waitcnt vmcnt(26)
	s_branch .Lmy_ln2d_copy

; template <int MODE, bool ROUTE, int H8> ...
;     ...
;             if (r + 1 < 32) LN_LOAD(r + 1);
.Lmy_ln2d_tail4:
	s_cmp_eq_u32 s42, 0
	s_cbranch_scc1 .Lmy_ln2d_Lmy_ln2d_tail4_first
	s_cmp_gt_u32 s42, 29
	s_cbranch_scc1 .Lmy_ln2d_Lmy_ln2d_tail4_last
	s_waitcnt vmcnt(16)
	s_branch .Lmy_ln2d_copy
.Lmy_ln2d_Lmy_ln2d_tail4_first:
	s_waitcnt vmcnt(12)
	s_branch .Lmy_ln2d_copy

; template <int MODE, bool ROUTE, int H8> ...
;     ...
;             if (r + 1 < 32) LN_LOAD(r + 1);
.LBB0_1276:
	s_or_b64 exec, exec, s[2:3]
.LBB0_1277:
	s_waitcnt vmcnt(0)
.Lmy_ln2d_copy:
	s_bitcmp1_b32 s42, 0
	s_cbranch_scc1 .Lmy_ln2d_copyB
	v_mov_b64_e32 v[84:85], v[132:133]
	v_mov_b64_e32 v[92:93], v[130:131]
	v_mov_b64_e32 v[88:89], v[128:129]
	v_mov_b64_e32 v[96:97], v[126:127]
	v_mov_b64_e32 v[86:87], v[134:135]
	v_mov_b64_e32 v[94:95], v[136:137]
	v_mov_b64_e32 v[90:91], v[138:139]
	v_mov_b64_e32 v[98:99], v[140:141]
	s_branch .Lmy_ln2d_next
.Lmy_ln2d_copyB:
	v_mov_b64_e32 v[84:85], v[186:187]
	v_mov_b64_e32 v[92:93], v[184:185]
	v_mov_b64_e32 v[88:89], v[182:183]
	v_mov_b64_e32 v[96:97], v[180:181]
	v_mov_b64_e32 v[86:87], v[188:189]
	v_mov_b64_e32 v[94:95], v[190:191]
	v_mov_b64_e32 v[90:91], v[192:193]
	v_mov_b64_e32 v[98:99], v[194:195]
.Lmy_ln2d_next:
	s_add_i32 s42, s42, 1
	s_cmp_eq_u32 s42, 32
	s_cbranch_scc1 .LBB0_1266
.LBB0_1278:
	s_add_i32 s10, s46, s42
	s_cmp_gt_u32 s42, 29
	s_cbranch_scc1 .LBB0_1280
	s_add_i32 s2, s10, 2
	s_bitcmp1_b32 s42, 0
	s_cbranch_scc1 .Lmy_ln2d_ldA
	s_ashr_i32 s3, s2, 31
	s_lshl_b64 s[2:3], s[2:3], 11
	v_lshl_add_u64 v[186:187], v[102:103], 0, s[2:3]
	v_lshl_add_u64 v[188:189], v[104:105], 0, s[2:3]
	global_load_dwordx2 v[180:181], v[186:187], off nt
	global_load_dwordx2 v[182:183], v[186:187], off offset:512 nt
	global_load_dwordx2 v[184:185], v[186:187], off offset:1024 nt
	s_nop 0
	global_load_dwordx2 v[186:187], v[186:187], off offset:1536 nt
	s_nop 0
	global_load_dwordx2 v[194:195], v[188:189], off
	global_load_dwordx2 v[192:193], v[188:189], off offset:512
	global_load_dwordx2 v[190:191], v[188:189], off offset:1024
	s_nop 0
	global_load_dwordx2 v[188:189], v[188:189], off offset:1536
	s_branch .LBB0_1280
.Lmy_ln2d_ldA:
	s_ashr_i32 s3, s2, 31
	s_lshl_b64 s[2:3], s[2:3], 11
	v_lshl_add_u64 v[132:133], v[102:103], 0, s[2:3]
	v_lshl_add_u64 v[134:135], v[104:105], 0, s[2:3]
	global_load_dwordx2 v[126:127], v[132:133], off nt
	global_load_dwordx2 v[128:129], v[132:133], off offset:512 nt
	global_load_dwordx2 v[130:131], v[132:133], off offset:1024 nt
	s_nop 0
	global_load_dwordx2 v[132:133], v[132:133], off offset:1536 nt
	s_nop 0
	global_load_dwordx2 v[140:141], v[134:135], off
	global_load_dwordx2 v[138:139], v[134:135], off offset:512
	global_load_dwordx2 v[136:137], v[134:135], off offset:1024
	s_nop 0
	global_load_dwordx2 v[134:135], v[134:135], off offset:1536
